# combo19 + P5: next unit's row-factor loads (SSQA/SSQB) issued with the epilogue's first load batch instead of behind its out-store drain
# speedup vs baseline: 1.0122x; 1.0042x over previous
.LBB0_1746:
	v_mov_b32_e32 v0, v222
	s_ashr_i32 s4, s28, 3
	s_lshl_b32 s5, s29, 8
	v_and_b32_e32 v193, 15, v0
	v_ashrrev_i32_e32 v0, 4, v0
	s_or_b32 s5, s5, s49
	s_mul_i32 s4, s4, 3
	v_readlane_b32 s30, v255, 8
	v_lshl_add_u32 v2, v0, 2, s5
	s_ashr_i32 s5, s4, 31
	s_lshl_b64 s[4:5], s[4:5], 14
	v_readlane_b32 s31, v255, 9
	s_add_u32 s4, s30, s4
	v_ashrrev_i32_e32 v3, 31, v2
	s_addc_u32 s5, s31, s5
	v_lshlrev_b64 v[2:3], 2, v[2:3]
	v_lshl_add_u64 v[132:133], s[4:5], 0, v[2:3]
	v_add_u32_e32 v0, s48, v193
	s_lshl_b32 s4, s28, 8
	v_add_u32_e32 v152, s4, v0
	v_ashrrev_i32_e32 v153, 31, v152
	v_lshl_add_u64 v[140:141], v[132:133], 0, s[16:17]
	v_add_co_u32_e32 v132, vcc, s52, v132
	v_lshlrev_b64 v[154:155], 14, v[152:153]
	s_nop 0
	v_addc_co_u32_e32 v133, vcc, 0, v133, vcc
	v_lshl_add_u64 v[136:137], s[36:37], 0, v[154:155]
	global_load_dwordx4 v[132:135], v[132:133], off
	v_lshl_add_u64 v[170:171], v[136:137], 0, v[2:3]
	global_load_dwordx4 v[148:151], v[170:171], off
	global_load_dwordx4 v[162:165], v[170:171], off offset:64
	global_load_dwordx4 v[144:147], v[140:141], off offset:64
	global_load_dwordx4 v[136:139], v[140:141], off offset:512
	global_load_dwordx4 v[166:169], v[170:171], off offset:512
	s_nop 0
	global_load_dwordx4 v[140:143], v[140:141], off offset:576
	s_nop 0
	global_load_dwordx4 v[170:173], v[170:171], off offset:576
	s_add_i32 s5, s4, s55
	v_add_u32_e32 v174, s5, v193
	v_ashrrev_i32_e32 v175, 31, v174
	v_lshlrev_b64 v[190:191], 14, v[174:175]
	v_lshl_add_u64 v[174:175], s[36:37], 0, v[190:191]
	v_lshl_add_u64 v[186:187], v[174:175], 0, v[2:3]
	global_load_dwordx4 v[174:177], v[186:187], off
	global_load_dwordx4 v[178:181], v[186:187], off offset:64
	global_load_dwordx4 v[182:185], v[186:187], off offset:512
	s_nop 0
	global_load_dwordx4 v[186:189], v[186:187], off offset:576
	s_add_i32 s5, s21, 0
	v_lshl_add_u32 v0, v0, 3, s5
	v_add_u32_e32 v0, 0x20000, v0
	s_and_b64 vcc, exec, s[0:1]
	s_cbranch_vccz .Lp5b_skip
	v_cmp_gt_i32_e32 vcc, s54, v252
	s_and_saveexec_b64 s[46:47], vcc
	v_lshl_add_u32 v212, s22, 8, v252
	v_ashrrev_i32_e32 v213, 31, v212
	v_lshlrev_b64 v[212:213], 6, v[212:213]
	v_lshl_add_u64 v[214:215], s[42:43], 0, v[212:213]
	v_lshl_add_u64 v[212:213], s[6:7], 0, v[212:213]
	global_load_dwordx4 v[224:227], v[212:213], off
	global_load_dwordx4 v[228:231], v[212:213], off offset:16
	global_load_dwordx4 v[232:235], v[212:213], off offset:32
	global_load_dwordx4 v[236:239], v[212:213], off offset:48
	global_load_dwordx4 v[240:243], v[214:215], off
	global_load_dwordx4 v[244:247], v[214:215], off offset:16
	global_load_dwordx4 v[248:251], v[214:215], off offset:32
	global_load_dwordx4 v[208:211], v[214:215], off offset:48
	s_or_b64 exec, exec, s[46:47]
.Lp5b_skip:
	s_waitcnt vmcnt(0)
	ds_read_b64 v[196:197], v0
	s_add_i32 s5, s4, s56
	s_add_i32 s4, s4, s57
	v_add_u32_e32 v192, s5, v193
	v_add_u32_e32 v194, s4, v193
	v_ashrrev_i32_e32 v193, 31, v192
	v_lshl_add_u64 v[154:155], s[68:69], 0, v[154:155]
	s_waitcnt lgkmcnt(0)
	v_pk_mul_f32 v[128:129], v[128:129], v[196:197] op_sel:[0,1]
	v_pk_mul_f32 v[130:131], v[130:131], v[196:197] op_sel:[0,1]
	v_lshlrev_b64 v[192:193], 14, v[192:193]
	v_lshl_add_u64 v[154:155], v[154:155], 0, v[2:3]
	v_pk_mul_f32 v[124:125], v[124:125], v[196:197] op_sel:[0,1]
	v_pk_mul_f32 v[126:127], v[126:127], v[196:197] op_sel:[0,1]
	v_pk_mul_f32 v[202:203], v[120:121], v[196:197] op_sel:[0,1]
	v_pk_mul_f32 v[204:205], v[122:123], v[196:197] op_sel:[0,1]
	v_pk_mul_f32 v[206:207], v[116:117], v[196:197] op_sel:[0,1]
	v_pk_mul_f32 v[196:197], v[118:119], v[196:197] op_sel:[0,1]
	v_lshl_add_u64 v[198:199], s[36:37], 0, v[192:193]
	v_lshl_add_u64 v[198:199], v[198:199], 0, v[2:3]
	v_ashrrev_i32_e32 v195, 31, v194
	v_lshl_add_u64 v[190:191], s[68:69], 0, v[190:191]
	v_lshlrev_b64 v[194:195], 14, v[194:195]
	v_lshl_add_u64 v[190:191], v[190:191], 0, v[2:3]
	v_lshl_add_u64 v[200:201], s[36:37], 0, v[194:195]
	s_andn2_b64 vcc, exec, s[0:1]
	s_mov_b64 s[0:1], -1
	v_pk_fma_f32 v[122:123], v[146:147], v[126:127], v[164:165]
	v_pk_fma_f32 v[120:121], v[144:145], v[124:125], v[162:163]
	v_pk_fma_f32 v[118:119], v[134:135], v[130:131], v[150:151]
	v_pk_fma_f32 v[116:117], v[132:133], v[128:129], v[148:149]
	v_pk_fma_f32 v[126:127], v[138:139], v[204:205], v[168:169]
	v_pk_fma_f32 v[124:125], v[136:137], v[202:203], v[166:167]
	v_pk_fma_f32 v[130:131], v[142:143], v[196:197], v[172:173]
	v_pk_fma_f32 v[128:129], v[140:141], v[206:207], v[170:171]
	global_store_dwordx4 v[154:155], v[116:119], off nt
	global_store_dwordx4 v[154:155], v[120:123], off offset:64 nt
	global_store_dwordx4 v[154:155], v[124:127], off offset:512 nt
	global_store_dwordx4 v[154:155], v[128:131], off offset:576 nt
	global_load_dwordx4 v[116:119], v[198:199], off
	global_load_dwordx4 v[120:123], v[198:199], off offset:64
	ds_read_b64 v[148:149], v0 offset:128
	global_load_dwordx4 v[124:127], v[198:199], off offset:512
	global_load_dwordx4 v[128:131], v[198:199], off offset:576
	v_lshl_add_u64 v[150:151], v[200:201], 0, v[2:3]
	s_waitcnt lgkmcnt(0)
	v_pk_mul_f32 v[112:113], v[112:113], v[148:149] op_sel:[0,1]
	v_pk_mul_f32 v[114:115], v[114:115], v[148:149] op_sel:[0,1]
	v_pk_mul_f32 v[108:109], v[108:109], v[148:149] op_sel:[0,1]
	v_pk_mul_f32 v[110:111], v[110:111], v[148:149] op_sel:[0,1]
	v_pk_mul_f32 v[154:155], v[104:105], v[148:149] op_sel:[0,1]
	v_pk_mul_f32 v[162:163], v[106:107], v[148:149] op_sel:[0,1]
	v_pk_mul_f32 v[164:165], v[100:101], v[148:149] op_sel:[0,1]
	v_pk_mul_f32 v[148:149], v[102:103], v[148:149] op_sel:[0,1]
	v_pk_fma_f32 v[102:103], v[134:135], v[114:115], v[176:177]
	v_pk_fma_f32 v[100:101], v[132:133], v[112:113], v[174:175]
	v_pk_fma_f32 v[106:107], v[146:147], v[110:111], v[180:181]
	v_pk_fma_f32 v[104:105], v[144:145], v[108:109], v[178:179]
	v_pk_fma_f32 v[110:111], v[138:139], v[162:163], v[184:185]
	v_pk_fma_f32 v[108:109], v[136:137], v[154:155], v[182:183]
	v_pk_fma_f32 v[114:115], v[142:143], v[148:149], v[188:189]
	v_pk_fma_f32 v[112:113], v[140:141], v[164:165], v[186:187]
	global_store_dwordx4 v[190:191], v[100:103], off nt
	global_store_dwordx4 v[190:191], v[104:107], off offset:64 nt
	global_store_dwordx4 v[190:191], v[108:111], off offset:512 nt
	global_store_dwordx4 v[190:191], v[112:115], off offset:576 nt
	global_load_dwordx4 v[100:103], v[150:151], off
	global_load_dwordx4 v[104:107], v[150:151], off offset:64
	global_load_dwordx4 v[108:111], v[150:151], off offset:512
	global_load_dwordx4 v[112:115], v[150:151], off offset:576
	ds_read_b64 v[166:167], v0 offset:256
	v_add_u32_e32 v148, 0x80, v152
	v_ashrrev_i32_e32 v149, 31, v148
	v_lshl_add_u64 v[154:155], s[68:69], 0, v[192:193]
	v_lshlrev_b64 v[148:149], 14, v[148:149]
	s_waitcnt lgkmcnt(0)
	v_pk_mul_f32 v[96:97], v[96:97], v[166:167] op_sel:[0,1]
	v_pk_mul_f32 v[98:99], v[98:99], v[166:167] op_sel:[0,1]
	v_lshl_add_u64 v[154:155], v[154:155], 0, v[2:3]
	v_pk_mul_f32 v[92:93], v[92:93], v[166:167] op_sel:[0,1]
	v_pk_mul_f32 v[94:95], v[94:95], v[166:167] op_sel:[0,1]
	v_pk_mul_f32 v[170:171], v[88:89], v[166:167] op_sel:[0,1]
	v_pk_mul_f32 v[172:173], v[90:91], v[166:167] op_sel:[0,1]
	v_pk_mul_f32 v[174:175], v[84:85], v[166:167] op_sel:[0,1]
	v_pk_mul_f32 v[166:167], v[86:87], v[166:167] op_sel:[0,1]
	v_lshl_add_u64 v[162:163], s[36:37], 0, v[148:149]
	v_lshl_add_u64 v[162:163], v[162:163], 0, v[2:3]
	v_add_u32_e32 v150, 0x90, v152
	v_ashrrev_i32_e32 v151, 31, v150
	v_lshl_add_u64 v[164:165], s[68:69], 0, v[194:195]
	v_lshlrev_b64 v[150:151], 14, v[150:151]
	v_lshl_add_u64 v[164:165], v[164:165], 0, v[2:3]
	v_lshl_add_u64 v[168:169], s[36:37], 0, v[150:151]
	s_waitcnt vmcnt(11)
	v_pk_fma_f32 v[86:87], v[134:135], v[98:99], v[118:119]
	v_pk_fma_f32 v[84:85], v[132:133], v[96:97], v[116:117]
	s_waitcnt vmcnt(10)
	v_pk_fma_f32 v[90:91], v[146:147], v[94:95], v[122:123]
	v_pk_fma_f32 v[88:89], v[144:145], v[92:93], v[120:121]
	s_waitcnt vmcnt(9)
	v_pk_fma_f32 v[94:95], v[138:139], v[172:173], v[126:127]
	v_pk_fma_f32 v[92:93], v[136:137], v[170:171], v[124:125]
	s_waitcnt vmcnt(8)
	v_pk_fma_f32 v[98:99], v[142:143], v[166:167], v[130:131]
	v_pk_fma_f32 v[96:97], v[140:141], v[174:175], v[128:129]
	global_store_dwordx4 v[154:155], v[84:87], off nt
	global_store_dwordx4 v[154:155], v[88:91], off offset:64 nt
	global_store_dwordx4 v[154:155], v[92:95], off offset:512 nt
	global_store_dwordx4 v[154:155], v[96:99], off offset:576 nt
	global_load_dwordx4 v[84:87], v[162:163], off
	global_load_dwordx4 v[88:91], v[162:163], off offset:64
	ds_read_b64 v[116:117], v0 offset:384
	global_load_dwordx4 v[92:95], v[162:163], off offset:512
	global_load_dwordx4 v[96:99], v[162:163], off offset:576
	v_lshl_add_u64 v[118:119], v[168:169], 0, v[2:3]
	s_waitcnt lgkmcnt(0)
	v_pk_mul_f32 v[80:81], v[80:81], v[116:117] op_sel:[0,1]
	v_pk_mul_f32 v[82:83], v[82:83], v[116:117] op_sel:[0,1]
	v_pk_mul_f32 v[76:77], v[76:77], v[116:117] op_sel:[0,1]
	v_pk_mul_f32 v[78:79], v[78:79], v[116:117] op_sel:[0,1]
	v_pk_mul_f32 v[120:121], v[72:73], v[116:117] op_sel:[0,1]
	v_pk_mul_f32 v[122:123], v[74:75], v[116:117] op_sel:[0,1]
	v_pk_mul_f32 v[124:125], v[68:69], v[116:117] op_sel:[0,1]
	v_pk_mul_f32 v[116:117], v[70:71], v[116:117] op_sel:[0,1]
	s_waitcnt vmcnt(11)
	v_pk_fma_f32 v[70:71], v[134:135], v[82:83], v[102:103]
	v_pk_fma_f32 v[68:69], v[132:133], v[80:81], v[100:101]
	s_waitcnt vmcnt(10)
	v_pk_fma_f32 v[74:75], v[146:147], v[78:79], v[106:107]
	v_pk_fma_f32 v[72:73], v[144:145], v[76:77], v[104:105]
	s_waitcnt vmcnt(9)
	v_pk_fma_f32 v[78:79], v[138:139], v[122:123], v[110:111]
	v_pk_fma_f32 v[76:77], v[136:137], v[120:121], v[108:109]
	s_waitcnt vmcnt(8)
	v_pk_fma_f32 v[82:83], v[142:143], v[116:117], v[114:115]
	v_pk_fma_f32 v[80:81], v[140:141], v[124:125], v[112:113]
	global_store_dwordx4 v[164:165], v[68:71], off nt
	global_store_dwordx4 v[164:165], v[72:75], off offset:64 nt
	global_store_dwordx4 v[164:165], v[76:79], off offset:512 nt
	global_store_dwordx4 v[164:165], v[80:83], off offset:576 nt
	global_load_dwordx4 v[68:71], v[118:119], off
	global_load_dwordx4 v[72:75], v[118:119], off offset:64
	global_load_dwordx4 v[76:79], v[118:119], off offset:512
	global_load_dwordx4 v[80:83], v[118:119], off offset:576
	ds_read_b64 v[110:111], v0 offset:1024
	v_add_u32_e32 v100, 0xa0, v152
	v_ashrrev_i32_e32 v101, 31, v100
	v_lshl_add_u64 v[104:105], s[68:69], 0, v[148:149]
	v_lshlrev_b64 v[100:101], 14, v[100:101]
	s_waitcnt lgkmcnt(0)
	v_pk_mul_f32 v[64:65], v[64:65], v[110:111] op_sel:[0,1]
	v_pk_mul_f32 v[66:67], v[66:67], v[110:111] op_sel:[0,1]
	v_lshl_add_u64 v[104:105], v[104:105], 0, v[2:3]
	v_pk_mul_f32 v[60:61], v[60:61], v[110:111] op_sel:[0,1]
	v_pk_mul_f32 v[62:63], v[62:63], v[110:111] op_sel:[0,1]
	v_pk_mul_f32 v[114:115], v[56:57], v[110:111] op_sel:[0,1]
	v_pk_mul_f32 v[116:117], v[58:59], v[110:111] op_sel:[0,1]
	v_pk_mul_f32 v[118:119], v[52:53], v[110:111] op_sel:[0,1]
	v_pk_mul_f32 v[110:111], v[54:55], v[110:111] op_sel:[0,1]
	v_lshl_add_u64 v[106:107], s[36:37], 0, v[100:101]
	v_lshl_add_u64 v[106:107], v[106:107], 0, v[2:3]
	v_add_u32_e32 v102, 0xb0, v152
	v_ashrrev_i32_e32 v103, 31, v102
	v_lshl_add_u64 v[108:109], s[68:69], 0, v[150:151]
	v_lshlrev_b64 v[102:103], 14, v[102:103]
	v_lshl_add_u64 v[108:109], v[108:109], 0, v[2:3]
	v_lshl_add_u64 v[112:113], s[36:37], 0, v[102:103]
	s_waitcnt vmcnt(11)
	v_pk_fma_f32 v[54:55], v[134:135], v[66:67], v[86:87]
	v_pk_fma_f32 v[52:53], v[132:133], v[64:65], v[84:85]
	s_waitcnt vmcnt(10)
	v_pk_fma_f32 v[58:59], v[146:147], v[62:63], v[90:91]
	v_pk_fma_f32 v[56:57], v[144:145], v[60:61], v[88:89]
	s_waitcnt vmcnt(9)
	v_pk_fma_f32 v[62:63], v[138:139], v[116:117], v[94:95]
	v_pk_fma_f32 v[60:61], v[136:137], v[114:115], v[92:93]
	s_waitcnt vmcnt(8)
	v_pk_fma_f32 v[66:67], v[142:143], v[110:111], v[98:99]
	v_pk_fma_f32 v[64:65], v[140:141], v[118:119], v[96:97]
	global_store_dwordx4 v[104:105], v[52:55], off nt
	global_store_dwordx4 v[104:105], v[56:59], off offset:64 nt
	global_store_dwordx4 v[104:105], v[60:63], off offset:512 nt
	global_store_dwordx4 v[104:105], v[64:67], off offset:576 nt
	global_load_dwordx4 v[52:55], v[106:107], off
	ds_read_b64 v[84:85], v0 offset:1152
	global_load_dwordx4 v[56:59], v[106:107], off offset:64
	global_load_dwordx4 v[60:63], v[106:107], off offset:512
	global_load_dwordx4 v[64:67], v[106:107], off offset:576
	v_lshl_add_u64 v[86:87], v[112:113], 0, v[2:3]
	s_waitcnt lgkmcnt(0)
	v_pk_mul_f32 v[48:49], v[48:49], v[84:85] op_sel:[0,1]
	v_pk_mul_f32 v[50:51], v[50:51], v[84:85] op_sel:[0,1]
	v_pk_mul_f32 v[44:45], v[44:45], v[84:85] op_sel:[0,1]
	v_pk_mul_f32 v[46:47], v[46:47], v[84:85] op_sel:[0,1]
	v_pk_mul_f32 v[88:89], v[40:41], v[84:85] op_sel:[0,1]
	v_pk_mul_f32 v[90:91], v[42:43], v[84:85] op_sel:[0,1]
	v_pk_mul_f32 v[92:93], v[36:37], v[84:85] op_sel:[0,1]
	v_pk_mul_f32 v[84:85], v[38:39], v[84:85] op_sel:[0,1]
	s_waitcnt vmcnt(11)
	v_pk_fma_f32 v[38:39], v[134:135], v[50:51], v[70:71]
	v_pk_fma_f32 v[36:37], v[132:133], v[48:49], v[68:69]
	s_waitcnt vmcnt(10)
	v_pk_fma_f32 v[42:43], v[146:147], v[46:47], v[74:75]
	v_pk_fma_f32 v[40:41], v[144:145], v[44:45], v[72:73]
	s_waitcnt vmcnt(9)
	v_pk_fma_f32 v[46:47], v[138:139], v[90:91], v[78:79]
	v_pk_fma_f32 v[44:45], v[136:137], v[88:89], v[76:77]
	s_waitcnt vmcnt(8)
	v_pk_fma_f32 v[50:51], v[142:143], v[84:85], v[82:83]
	v_pk_fma_f32 v[48:49], v[140:141], v[92:93], v[80:81]
	global_store_dwordx4 v[108:109], v[36:39], off nt
	global_store_dwordx4 v[108:109], v[40:43], off offset:64 nt
	global_store_dwordx4 v[108:109], v[44:47], off offset:512 nt
	global_store_dwordx4 v[108:109], v[48:51], off offset:576 nt
	global_load_dwordx4 v[36:39], v[86:87], off
	global_load_dwordx4 v[40:43], v[86:87], off offset:64
	global_load_dwordx4 v[44:47], v[86:87], off offset:512
	global_load_dwordx4 v[48:51], v[86:87], off offset:576
	ds_read_b64 v[68:69], v0 offset:1280
	v_lshl_add_u64 v[70:71], s[68:69], 0, v[100:101]
	v_lshl_add_u64 v[70:71], v[70:71], 0, v[2:3]
	s_waitcnt lgkmcnt(0)
	v_pk_mul_f32 v[32:33], v[32:33], v[68:69] op_sel:[0,1]
	v_pk_mul_f32 v[34:35], v[34:35], v[68:69] op_sel:[0,1]
	v_pk_mul_f32 v[28:29], v[28:29], v[68:69] op_sel:[0,1]
	v_pk_mul_f32 v[30:31], v[30:31], v[68:69] op_sel:[0,1]
	v_pk_mul_f32 v[72:73], v[24:25], v[68:69] op_sel:[0,1]
	v_pk_mul_f32 v[74:75], v[26:27], v[68:69] op_sel:[0,1]
	v_pk_mul_f32 v[76:77], v[20:21], v[68:69] op_sel:[0,1]
	v_pk_mul_f32 v[68:69], v[22:23], v[68:69] op_sel:[0,1]
	s_waitcnt vmcnt(10)
	v_pk_fma_f32 v[26:27], v[146:147], v[30:31], v[58:59]
	v_pk_fma_f32 v[22:23], v[134:135], v[34:35], v[54:55]
	v_pk_fma_f32 v[20:21], v[132:133], v[32:33], v[52:53]
	v_pk_fma_f32 v[24:25], v[144:145], v[28:29], v[56:57]
	s_waitcnt vmcnt(9)
	v_pk_fma_f32 v[30:31], v[138:139], v[74:75], v[62:63]
	v_pk_fma_f32 v[28:29], v[136:137], v[72:73], v[60:61]
	s_waitcnt vmcnt(8)
	v_pk_fma_f32 v[34:35], v[142:143], v[68:69], v[66:67]
	v_pk_fma_f32 v[32:33], v[140:141], v[76:77], v[64:65]
	global_store_dwordx4 v[70:71], v[20:23], off nt
	global_store_dwordx4 v[70:71], v[24:27], off offset:64 nt
	global_store_dwordx4 v[70:71], v[28:31], off offset:512 nt
	global_store_dwordx4 v[70:71], v[32:35], off offset:576 nt
	ds_read_b64 v[20:21], v0 offset:1408
	v_lshl_add_u64 v[22:23], s[68:69], 0, v[102:103]
	v_lshl_add_u64 v[22:23], v[22:23], 0, v[2:3]
	s_waitcnt lgkmcnt(0)
	v_pk_mul_f32 v[2:3], v[16:17], v[20:21] op_sel:[0,1]
	v_pk_mul_f32 v[16:17], v[18:19], v[20:21] op_sel:[0,1]
	v_pk_mul_f32 v[12:13], v[12:13], v[20:21] op_sel:[0,1]
	v_pk_mul_f32 v[14:15], v[14:15], v[20:21] op_sel:[0,1]
	v_pk_mul_f32 v[18:19], v[8:9], v[20:21] op_sel:[0,1]
	v_pk_mul_f32 v[10:11], v[10:11], v[20:21] op_sel:[0,1]
	v_pk_mul_f32 v[24:25], v[4:5], v[20:21] op_sel:[0,1]
	v_pk_mul_f32 v[20:21], v[6:7], v[20:21] op_sel:[0,1]
	s_waitcnt vmcnt(7)
	v_pk_fma_f32 v[4:5], v[134:135], v[16:17], v[38:39]
	v_pk_fma_f32 v[2:3], v[132:133], v[2:3], v[36:37]
	s_waitcnt vmcnt(6)
	v_pk_fma_f32 v[8:9], v[146:147], v[14:15], v[42:43]
	v_pk_fma_f32 v[6:7], v[144:145], v[12:13], v[40:41]
	s_waitcnt vmcnt(5)
	v_pk_fma_f32 v[12:13], v[138:139], v[10:11], v[46:47]
	v_pk_fma_f32 v[10:11], v[136:137], v[18:19], v[44:45]
	s_waitcnt vmcnt(4)
	v_pk_fma_f32 v[16:17], v[142:143], v[20:21], v[50:51]
	v_pk_fma_f32 v[14:15], v[140:141], v[24:25], v[48:49]
	global_store_dwordx4 v[22:23], v[2:5], off nt
	global_store_dwordx4 v[22:23], v[6:9], off offset:64 nt
	global_store_dwordx4 v[22:23], v[10:13], off offset:512 nt
	global_store_dwordx4 v[22:23], v[14:17], off offset:576 nt
	s_cbranch_vccnz .LBB0_1733
	v_mov_b32_e32 v0, v252
	s_nop 0
	v_cmp_gt_i32_e32 vcc, s54, v0
	s_and_saveexec_b64 s[28:29], vcc
	s_cbranch_execz .LBB0_1749
	s_lshl_b32 s0, s62, 11
	s_and_b32 s0, s0, 0x800
	s_add_i32 s4, s0, 0
	v_lshl_add_u32 v0, v0, 3, s4
	v_add_u32_e32 v0, 0x20000, v0
	v_pk_add_f32 v[4:5], v[226:227], v[230:231]
	v_pk_add_f32 v[2:3], v[224:225], v[228:229]
	v_pk_add_f32 v[6:7], v[234:235], v[238:239]
	v_pk_add_f32 v[8:9], v[232:233], v[236:237]
	v_pk_add_f32 v[10:11], v[242:243], v[246:247]
	v_pk_add_f32 v[12:13], v[240:241], v[244:245]
	v_pk_add_f32 v[14:15], v[250:251], v[210:211]
	v_pk_add_f32 v[16:17], v[248:249], v[208:209]
	v_pk_add_f32 v[4:5], v[4:5], v[6:7]
	v_pk_add_f32 v[2:3], v[2:3], v[8:9]
	v_pk_add_f32 v[6:7], v[10:11], v[14:15]
	v_pk_add_f32 v[8:9], v[12:13], v[16:17]
	s_nop 0
	v_pk_mov_b32 v[10:11], v[8:9], v[6:7] op_sel:[1,0]
	v_mov_b32_e32 v9, v7
	v_pk_mov_b32 v[6:7], v[2:3], v[4:5] op_sel:[1,0]
	v_mov_b32_e32 v3, v5
	v_pk_add_f32 v[4:5], v[10:11], v[8:9]
	v_pk_add_f32 v[2:3], v[6:7], v[2:3]
	v_add_f32_e32 v4, v4, v5
	v_mov_b32_e32 v5, 0x358637bd
	v_add_f32_e32 v2, v2, v3
	v_fmamk_f32 v3, v4, 0x3a000000, v5
	v_fmamk_f32 v2, v2, 0x3a000000, v5
	v_mul_f32_e32 v4, 0x4f800000, v3
	v_cmp_gt_f32_e32 vcc, s61, v3
	v_mul_f32_e32 v5, 0x4f800000, v2
	v_cmp_gt_f32_e64 s[0:1], s61, v2
	v_cndmask_b32_e32 v3, v3, v4, vcc
	v_sqrt_f32_e32 v4, v3
	v_cndmask_b32_e64 v2, v2, v5, s[0:1]
	v_sqrt_f32_e32 v5, v2
	v_add_u32_e32 v6, -1, v4
	v_fma_f32 v10, -v6, v4, v3
	v_add_u32_e32 v8, -1, v5
	v_add_u32_e32 v7, 1, v4
	v_fma_f32 v12, -v8, v5, v2
	v_cmp_ge_f32_e64 s[4:5], 0, v10
	v_add_u32_e32 v9, 1, v5
	v_fma_f32 v11, -v7, v4, v3
	v_cndmask_b32_e64 v4, v4, v6, s[4:5]
	v_cmp_ge_f32_e64 s[4:5], 0, v12
	v_fma_f32 v13, -v9, v5, v2
	s_nop 0
	v_cndmask_b32_e64 v5, v5, v8, s[4:5]
	v_cmp_lt_f32_e64 s[4:5], 0, v11
	s_nop 1
	v_cndmask_b32_e64 v4, v4, v7, s[4:5]
	v_cmp_lt_f32_e64 s[4:5], 0, v13
	v_mul_f32_e32 v6, 0x37800000, v4
	v_cndmask_b32_e32 v4, v4, v6, vcc
	v_cndmask_b32_e64 v5, v5, v9, s[4:5]
	v_mul_f32_e32 v7, 0x37800000, v5
	v_cmp_class_f32_e32 vcc, v3, v253
	v_cndmask_b32_e64 v5, v5, v7, s[0:1]
	s_nop 0
	v_cndmask_b32_e32 v4, v4, v3, vcc
	v_cmp_class_f32_e32 vcc, v2, v253
	v_div_scale_f32 v6, s[0:1], v4, v4, 1.0
	s_nop 0
	v_cndmask_b32_e32 v2, v5, v2, vcc
	v_div_scale_f32 v3, s[0:1], v2, v2, 1.0
	v_rcp_f32_e32 v7, v3
	v_rcp_f32_e32 v8, v6
	v_div_scale_f32 v5, vcc, 1.0, v2, 1.0
	v_fma_f32 v10, -v3, v7, 1.0
	v_fma_f32 v11, -v6, v8, 1.0
	v_fmac_f32_e32 v7, v10, v7
	v_div_scale_f32 v9, s[0:1], 1.0, v4, 1.0
	v_fmac_f32_e32 v8, v11, v8
	v_mul_f32_e32 v10, v5, v7
	v_mul_f32_e32 v11, v9, v8
	v_fma_f32 v12, -v3, v10, v5
	v_fma_f32 v13, -v6, v11, v9
	v_fmac_f32_e32 v10, v12, v7
	v_fmac_f32_e32 v11, v13, v8
	v_fma_f32 v3, -v3, v10, v5
	v_fma_f32 v5, -v6, v11, v9
	v_div_fmas_f32 v3, v3, v7, v10
	s_mov_b64 vcc, s[0:1]
	v_div_fixup_f32 v3, v3, v2, 1.0
	v_div_fmas_f32 v2, v5, v8, v11
	v_div_fixup_f32 v2, v2, v4, 1.0
	v_pk_mul_f32 v[4:5], v[2:3], s[18:19]
	v_mul_f32_e32 v3, 0x39000000, v3
	v_div_scale_f32 v2, s[0:1], v5, v5, v4
	v_rcp_f32_e32 v6, v2
	v_div_scale_f32 v7, vcc, v4, v5, v4
	v_fma_f32 v8, -v2, v6, 1.0
	v_fmac_f32_e32 v6, v8, v6
	v_mul_f32_e32 v8, v7, v6
	v_fma_f32 v9, -v2, v8, v7
	v_fmac_f32_e32 v8, v9, v6
	v_fma_f32 v2, -v2, v8, v7
	v_div_fmas_f32 v2, v2, v6, v8
	v_div_fixup_f32 v2, v2, v5, v4
	ds_write_b64 v0, v[2:3]
